# forgetting-attention main loop: the 5 LDS-DMA issues per step (and their scalar address math) moved from the step head into the QK^T MFMA stream
# speedup vs baseline: 1.0001x; 1.0001x over previous
.LBB0_1169:
	s_mov_b32 s61, s53
	s_mov_b32 s53, s65
	s_ashr_i32 s8, s61, 8
	v_lshl_add_u32 v1, s8, 2, v128
	ds_read_b128 v[96:99], v1
	ds_read_b128 v[100:103], v1 offset:32
	ds_read_b128 v[80:83], v1 offset:128
	ds_read_b128 v[84:87], v1 offset:160
	ds_read_b128 v[104:107], v1 offset:64
	ds_read_b128 v[108:111], v1 offset:96
	ds_read_b128 v[88:91], v1 offset:192
	ds_read_b128 v[92:95], v1 offset:224
	s_add_i32 s8, s61, 0
	v_add3_u32 v1, s8, v197, v196
	v_add3_u32 v6, s8, v198, v196
	v_add3_u32 v7, s8, v199, v196
	v_add3_u32 v8, s8, v200, v196
	s_setprio 1
	ds_read_b128 v[2:5], v1 offset:49152
	ds_read_b128 v[220:223], v1 offset:57344
	ds_read_b128 v[224:227], v6 offset:49152
	ds_read_b128 v[228:231], v6 offset:57344
	ds_read_b128 v[232:235], v7 offset:49152
	s_waitcnt lgkmcnt(4)
	v_mfma_f32_32x32x16_bf16 v[96:111], v[2:5], v[172:175], v[96:111]
	ds_read_b128 v[2:5], v7 offset:57344
	s_waitcnt lgkmcnt(4)
	v_mfma_f32_32x32x16_bf16 v[80:95], v[220:223], v[172:175], v[80:95]
	ds_read_b128 v[220:223], v8 offset:49152
	s_ashr_i32 s65, s64, 31
	s_lshl_b64 s[66:67], s[64:65], 14
	s_add_u32 s8, s54, s66
	s_addc_u32 s9, s55, s67
	s_add_i32 s70, s53, s90
	s_mov_b32 s71, m0
	s_mov_b32 m0, s70
	s_nop 0
	global_load_lds_dwordx4 v183, s[8:9]
	s_mov_b32 m0, s71
	s_waitcnt lgkmcnt(4)
	v_mfma_f32_32x32x16_bf16 v[96:111], v[224:227], v[168:171], v[96:111]
	ds_read_b128 v[224:227], v8 offset:57344
	s_waitcnt lgkmcnt(4)
	v_mfma_f32_32x32x16_bf16 v[80:95], v[228:231], v[168:171], v[80:95]
	ds_read_b128 v[228:231], v1 offset:49280
	s_waitcnt lgkmcnt(4)
	v_mfma_f32_32x32x16_bf16 v[96:111], v[232:235], v[164:167], v[96:111]
	ds_read_b128 v[232:235], v1 offset:57472
	s_addk_i32 s70, 0x400
	s_mov_b32 s71, m0
	s_mov_b32 m0, s70
	s_nop 0
	global_load_lds_dwordx4 v184, s[8:9]
	s_mov_b32 m0, s71
	s_waitcnt lgkmcnt(4)
	v_mfma_f32_32x32x16_bf16 v[80:95], v[2:5], v[164:167], v[80:95]
	ds_read_b128 v[2:5], v6 offset:49280
	s_waitcnt lgkmcnt(4)
	v_mfma_f32_32x32x16_bf16 v[96:111], v[220:223], v[160:163], v[96:111]
	ds_read_b128 v[220:223], v6 offset:57472
	s_waitcnt lgkmcnt(4)
	v_mfma_f32_32x32x16_bf16 v[80:95], v[224:227], v[160:163], v[80:95]
	ds_read_b128 v[224:227], v7 offset:49280
	s_lshl_b64 s[8:9], s[64:65], 8
	s_add_u32 s8, s58, s8
	s_addc_u32 s9, s59, s9
	s_ashr_i32 s65, s53, 6
	s_cmp_lg_u32 0, -1
	s_cselect_b32 s70, 0, 0
	s_add_i32 s65, s70, s65
	s_add_i32 s65, s65, 0x18800
	s_mov_b32 s70, m0
	s_mov_b32 m0, s65
	s_nop 0
	global_load_lds_dword v185, s[8:9]
	s_mov_b32 m0, s70
	s_waitcnt lgkmcnt(4)
	v_mfma_f32_32x32x16_bf16 v[96:111], v[228:231], v[156:159], v[96:111]
	ds_read_b128 v[228:231], v7 offset:57472
	s_waitcnt lgkmcnt(4)
	v_mfma_f32_32x32x16_bf16 v[80:95], v[232:235], v[156:159], v[80:95]
	ds_read_b128 v[232:235], v8 offset:49280
	s_waitcnt lgkmcnt(4)
	v_mfma_f32_32x32x16_bf16 v[96:111], v[2:5], v[152:155], v[96:111]
	ds_read_b128 v[2:5], v8 offset:57472
	s_add_i32 s8, s64, 1
	s_ashr_i32 s9, s8, 31
	s_lshl_b64 s[8:9], s[8:9], 14
	s_add_u32 s8, s56, s8
	s_addc_u32 s9, s57, s9
	s_add_i32 s65, s68, s83
	s_mov_b32 s70, m0
	s_mov_b32 m0, s65
	s_nop 0
	global_load_lds_dwordx4 v187, s[8:9]
	s_mov_b32 m0, s70
	s_waitcnt lgkmcnt(4)
	v_mfma_f32_32x32x16_bf16 v[80:95], v[220:223], v[152:155], v[80:95]
	s_waitcnt lgkmcnt(3)
	v_mfma_f32_32x32x16_bf16 v[96:111], v[224:227], v[148:151], v[96:111]
	s_waitcnt lgkmcnt(2)
	v_mfma_f32_32x32x16_bf16 v[80:95], v[228:231], v[148:151], v[80:95]
	s_addk_i32 s65, 0x400
	s_mov_b32 s70, m0
	s_mov_b32 m0, s65
	s_nop 0
	global_load_lds_dwordx4 v186, s[8:9]
	s_mov_b32 m0, s70
	s_waitcnt lgkmcnt(1)
	v_mfma_f32_32x32x16_bf16 v[96:111], v[232:235], v[144:147], v[96:111]
	s_waitcnt lgkmcnt(0)
	v_mfma_f32_32x32x16_bf16 v[80:95], v[2:5], v[144:147], v[80:95]
	s_setprio 0
	v_add_f32_e32 v1, 0, v215
	v_add_f32_e32 v1, v217, v1
	v_add_f32_e32 v1, v213, v1
	v_add_f32_e32 v1, v216, v1
	v_add_f32_e32 v1, v211, v1
	v_add_f32_e32 v1, v214, v1
	v_add_f32_e32 v1, v210, v1
	v_add_f32_e32 v1, v212, v1
	v_add_f32_e32 v1, v205, v1
	v_add_f32_e32 v1, v208, v1
	v_add_f32_e32 v1, v203, v1
	v_add_f32_e32 v1, v206, v1
	v_exp_f32_e32 v2, v126
	v_add_f32_e32 v1, v202, v1
	v_exp_f32_e32 v12, v127
	v_add_f32_e32 v1, v209, v1
	v_exp_f32_e32 v13, v124
	v_add_f32_e32 v1, v204, v1
	v_exp_f32_e32 v14, v125
	v_add_f32_e32 v1, v207, v1
	v_exp_f32_e32 v15, v122
	v_add_f32_e32 v1, v2, v1
	v_exp_f32_e32 v122, v123
	v_add_f32_e32 v1, v12, v1
	v_exp_f32_e32 v120, v120
	v_add_f32_e32 v1, v13, v1
	v_exp_f32_e32 v121, v121
	v_add_f32_e32 v1, v14, v1
	v_exp_f32_e32 v118, v118
	v_add_f32_e32 v1, v15, v1
	v_exp_f32_e32 v119, v119
	v_add_f32_e32 v1, v122, v1
	v_exp_f32_e32 v116, v116
	v_add_f32_e32 v1, v120, v1
	v_exp_f32_e32 v117, v117
	v_add_f32_e32 v1, v121, v1
	v_exp_f32_e32 v114, v114
	v_add_f32_e32 v1, v118, v1
	v_exp_f32_e32 v115, v115
	v_add_f32_e32 v1, v119, v1
	v_exp_f32_e32 v123, v112
	v_add_f32_e32 v1, v116, v1
	v_exp_f32_e32 v124, v113
	v_add_f32_e32 v1, v117, v1
	v_add_f32_e32 v1, v114, v1
	v_add_f32_e32 v1, v115, v1
	v_add_f32_e32 v1, v123, v1
	v_add_f32_e32 v1, v124, v1
	v_mov_b32_e32 v3, v1
	s_nop 1
	v_permlane32_swap_b32_e32 v1, v3
	v_cvt_pk_bf16_f32 v4, v215, v217
	v_cvt_pk_bf16_f32 v5, v213, v216
	v_cvt_pk_bf16_f32 v6, v211, v214
	v_cvt_pk_bf16_f32 v7, v210, v212
	v_cvt_pk_bf16_f32 v8, v205, v208
	v_cvt_pk_bf16_f32 v9, v203, v206
	v_cvt_pk_bf16_f32 v10, v202, v209
	v_cvt_pk_bf16_f32 v11, v204, v207
	v_cvt_pk_bf16_f32 v12, v2, v12
	v_cvt_pk_bf16_f32 v13, v13, v14
	v_cvt_pk_bf16_f32 v14, v15, v122
	v_cvt_pk_bf16_f32 v15, v120, v121
	v_cvt_pk_bf16_f32 v112, v118, v119
	v_cvt_pk_bf16_f32 v113, v116, v117
	v_cvt_pk_bf16_f32 v114, v114, v115
	v_cvt_pk_bf16_f32 v115, v123, v124
	s_nop 0
	v_add_u32_e32 v2, s53, v193
	ds_read_b64_tr_b16 v[116:117], v2 offset:0
	ds_read_b64_tr_b16 v[118:119], v2 offset:0x800
	ds_read_b64_tr_b16 v[120:121], v2 offset:0x1000
	ds_read_b64_tr_b16 v[122:123], v2 offset:0x1800
	ds_read_b64_tr_b16 v[124:125], v2 offset:0x2000
	ds_read_b64_tr_b16 v[126:127], v2 offset:0x2800
	ds_read_b64_tr_b16 v[132:133], v2 offset:0x3000
	ds_read_b64_tr_b16 v[134:135], v2 offset:0x3800
	s_waitcnt lgkmcnt(6)
	s_nop 0
	v_mfma_f32_32x32x16_bf16 v[16:31], v[4:7], v[116:119], v[16:31]
	ds_read_b64_tr_b16 v[116:117], v2 offset:0x200
	ds_read_b64_tr_b16 v[118:119], v2 offset:0xa00
	s_waitcnt lgkmcnt(6)
	v_mfma_f32_32x32x16_bf16 v[16:31], v[8:11], v[120:123], v[16:31]
	ds_read_b64_tr_b16 v[120:121], v2 offset:0x1200
	ds_read_b64_tr_b16 v[122:123], v2 offset:0x1a00
	s_waitcnt lgkmcnt(6)
	v_mfma_f32_32x32x16_bf16 v[16:31], v[12:15], v[124:127], v[16:31]
	ds_read_b64_tr_b16 v[124:125], v2 offset:0x2200
	ds_read_b64_tr_b16 v[126:127], v2 offset:0x2a00
	s_waitcnt lgkmcnt(6)
	v_mfma_f32_32x32x16_bf16 v[16:31], v[112:115], v[132:135], v[16:31]
	ds_read_b64_tr_b16 v[132:133], v2 offset:0x3200
	ds_read_b64_tr_b16 v[134:135], v2 offset:0x3a00
	s_waitcnt lgkmcnt(6)
	v_mfma_f32_32x32x16_bf16 v[48:63], v[4:7], v[116:119], v[48:63]
	ds_read_b64_tr_b16 v[116:117], v2 offset:0x400
	ds_read_b64_tr_b16 v[118:119], v2 offset:0xc00
	s_waitcnt lgkmcnt(6)
	v_mfma_f32_32x32x16_bf16 v[48:63], v[8:11], v[120:123], v[48:63]
	ds_read_b64_tr_b16 v[120:121], v2 offset:0x1400
	ds_read_b64_tr_b16 v[122:123], v2 offset:0x1c00
	s_waitcnt lgkmcnt(6)
	v_mfma_f32_32x32x16_bf16 v[48:63], v[12:15], v[124:127], v[48:63]
	ds_read_b64_tr_b16 v[124:125], v2 offset:0x2400
	ds_read_b64_tr_b16 v[126:127], v2 offset:0x2c00
	s_waitcnt lgkmcnt(6)
	v_mfma_f32_32x32x16_bf16 v[48:63], v[112:115], v[132:135], v[48:63]
	ds_read_b64_tr_b16 v[132:133], v2 offset:0x3400
	ds_read_b64_tr_b16 v[134:135], v2 offset:0x3c00
	s_waitcnt lgkmcnt(6)
	v_mfma_f32_32x32x16_bf16 v[64:79], v[4:7], v[116:119], v[64:79]
	ds_read_b64_tr_b16 v[116:117], v2 offset:0x600
	ds_read_b64_tr_b16 v[118:119], v2 offset:0xe00
	s_waitcnt lgkmcnt(6)
	v_mfma_f32_32x32x16_bf16 v[64:79], v[8:11], v[120:123], v[64:79]
	ds_read_b64_tr_b16 v[120:121], v2 offset:0x1600
	ds_read_b64_tr_b16 v[122:123], v2 offset:0x1e00
	s_waitcnt lgkmcnt(6)
	v_mfma_f32_32x32x16_bf16 v[64:79], v[12:15], v[124:127], v[64:79]
	ds_read_b64_tr_b16 v[124:125], v2 offset:0x2600
	ds_read_b64_tr_b16 v[126:127], v2 offset:0x2e00
	s_waitcnt lgkmcnt(6)
	v_mfma_f32_32x32x16_bf16 v[64:79], v[112:115], v[132:135], v[64:79]
	ds_read_b64_tr_b16 v[132:133], v2 offset:0x3600
	ds_read_b64_tr_b16 v[134:135], v2 offset:0x3e00
	s_waitcnt lgkmcnt(6)
	v_mfma_f32_32x32x16_bf16 v[32:47], v[4:7], v[116:119], v[32:47]
	s_add_i32 s8, s91, 64
	s_cmp_le_i32 s8, s69
	s_waitcnt lgkmcnt(4)
	v_mfma_f32_32x32x16_bf16 v[32:47], v[8:11], v[120:123], v[32:47]
	s_waitcnt lgkmcnt(2)
	v_mfma_f32_32x32x16_bf16 v[32:47], v[12:15], v[124:127], v[32:47]
	s_waitcnt lgkmcnt(0)
	v_mfma_f32_32x32x16_bf16 v[32:47], v[112:115], v[132:135], v[32:47]
	s_cbranch_scc1 .LBB0_1171
	v_add_u32_e32 v2, 0x4000003b, v130
	v_cmp_gt_u32_e32 vcc, 2.0, v2
	v_add_u32_e32 v2, 27, v130
	s_nop 0
	v_cndmask_b32_e32 v96, v179, v96, vcc
	v_cmp_lt_u32_e32 vcc, s96, v2
	v_add_u32_e32 v2, 58, v130
	s_nop 0
	v_cndmask_b32_e32 v80, v179, v80, vcc
	v_cmp_lt_u32_e32 vcc, s96, v2
	v_add_u32_e32 v2, 26, v130
	s_nop 0
	v_cndmask_b32_e32 v97, v179, v97, vcc
	v_cmp_lt_u32_e32 vcc, s96, v2
	v_add_u32_e32 v2, 57, v130
	s_nop 0
	v_cndmask_b32_e32 v81, v179, v81, vcc
	v_cmp_lt_u32_e32 vcc, s96, v2
	v_add_u32_e32 v2, 25, v130
	s_nop 0
	v_cndmask_b32_e32 v98, v179, v98, vcc
	v_cmp_lt_u32_e32 vcc, s96, v2
	v_add_u32_e32 v2, 56, v130
	s_nop 0
	v_cndmask_b32_e32 v82, v179, v82, vcc
	v_cmp_lt_u32_e32 vcc, s96, v2
	v_add_u32_e32 v2, 24, v130
	s_nop 0
	v_cndmask_b32_e32 v99, v179, v99, vcc
	v_cmp_lt_u32_e32 vcc, s96, v2
	v_add_u32_e32 v2, 51, v130
	s_nop 0
	v_cndmask_b32_e32 v83, v179, v83, vcc
	v_cmp_lt_u32_e32 vcc, s96, v2
	v_add_u32_e32 v2, 19, v130
	s_nop 0
	v_cndmask_b32_e32 v100, v179, v100, vcc
	v_cmp_lt_u32_e32 vcc, s96, v2
	v_add_u32_e32 v2, 50, v130
	s_nop 0
	v_cndmask_b32_e32 v84, v179, v84, vcc
	v_cmp_lt_u32_e32 vcc, s96, v2
	v_add_u32_e32 v2, 18, v130
	s_nop 0
	v_cndmask_b32_e32 v101, v179, v101, vcc
	v_cmp_lt_u32_e32 vcc, s96, v2
	v_add_u32_e32 v2, 49, v130
	s_nop 0
	v_cndmask_b32_e32 v85, v179, v85, vcc
	v_cmp_lt_u32_e32 vcc, s96, v2
	v_add_u32_e32 v2, 17, v130
	s_nop 0
	v_cndmask_b32_e32 v102, v179, v102, vcc
	v_cmp_lt_u32_e32 vcc, s96, v2
	v_add_u32_e32 v2, 48, v130
	s_nop 0
	v_cndmask_b32_e32 v86, v179, v86, vcc
	v_cmp_lt_u32_e32 vcc, s96, v2
	v_add_u32_e32 v2, 16, v130
	s_nop 0
	v_cndmask_b32_e32 v103, v179, v103, vcc
	v_cmp_lt_u32_e32 vcc, s96, v2
	v_add_u32_e32 v2, 43, v130
	s_nop 0
	v_cndmask_b32_e32 v87, v179, v87, vcc
	v_cmp_lt_u32_e32 vcc, s96, v2
	v_add_u32_e32 v2, 11, v130
	s_nop 0
	v_cndmask_b32_e32 v104, v179, v104, vcc
	v_cmp_lt_u32_e32 vcc, s96, v2
	v_add_u32_e32 v2, 42, v130
	s_nop 0
	v_cndmask_b32_e32 v88, v179, v88, vcc
	v_cmp_lt_u32_e32 vcc, s96, v2
	v_add_u32_e32 v2, 10, v130
	s_nop 0
	v_cndmask_b32_e32 v105, v179, v105, vcc
	v_cmp_lt_u32_e32 vcc, s96, v2
	v_add_u32_e32 v2, 41, v130
	s_nop 0
	v_cndmask_b32_e32 v89, v179, v89, vcc
	v_cmp_lt_u32_e32 vcc, s96, v2
	v_add_u32_e32 v2, 9, v130
	s_nop 0
	v_cndmask_b32_e32 v106, v179, v106, vcc
	v_cmp_lt_u32_e32 vcc, s96, v2
	v_add_u32_e32 v2, 40, v130
	s_nop 0
	v_cndmask_b32_e32 v90, v179, v90, vcc
	v_cmp_lt_u32_e32 vcc, s96, v2
	v_add_u32_e32 v2, 8, v130
	s_nop 0
	v_cndmask_b32_e32 v107, v179, v107, vcc
	v_cmp_lt_u32_e32 vcc, s96, v2
	v_add_u32_e32 v2, 35, v130
	s_nop 0
	v_cndmask_b32_e32 v91, v179, v91, vcc
	v_cmp_lt_u32_e32 vcc, s96, v2
	v_add_u32_e32 v2, 3, v130
	s_nop 0
	v_cndmask_b32_e32 v108, v179, v108, vcc
	v_cmp_lt_u32_e32 vcc, s96, v2
	v_add_u32_e32 v2, 34, v130
	s_nop 0
	v_cndmask_b32_e32 v92, v179, v92, vcc
	v_cmp_lt_u32_e32 vcc, s96, v2
	v_add_u32_e32 v2, 2, v130
	s_nop 0
	v_cndmask_b32_e32 v109, v179, v109, vcc
	v_cmp_lt_u32_e32 vcc, s96, v2
	v_add_u32_e32 v2, 33, v130
	s_nop 0
	v_cndmask_b32_e32 v93, v179, v93, vcc
	v_cmp_lt_u32_e32 vcc, s96, v2
	v_add_u32_e32 v2, 1, v130
	s_nop 0
	v_cndmask_b32_e32 v110, v179, v110, vcc
	v_cmp_lt_u32_e32 vcc, s96, v2
	v_add_u32_e32 v2, 32, v130
	s_nop 0
	v_cndmask_b32_e32 v94, v179, v94, vcc
	v_cmp_lt_u32_e32 vcc, s96, v2
	s_nop 1
	v_cndmask_b32_e32 v111, v179, v111, vcc
	v_cmp_lt_u32_e32 vcc, s96, v130
	s_nop 1
	v_cndmask_b32_e32 v95, v179, v95, vcc

.LBB0_1175:
	s_waitcnt vmcnt(5) lgkmcnt(0)
	s_barrier
	v_mul_f32_e32 v5, 0xbe0293ee, v2
	v_fmamk_f32 v6, v96, 0x3e0293ee, v5
	v_fmamk_f32 v7, v97, 0x3e0293ee, v5
	v_fmamk_f32 v8, v98, 0x3e0293ee, v5
	v_fmamk_f32 v9, v99, 0x3e0293ee, v5
	v_fmamk_f32 v10, v100, 0x3e0293ee, v5
	v_fmamk_f32 v11, v101, 0x3e0293ee, v5
	v_fmamk_f32 v12, v102, 0x3e0293ee, v5
	v_fmamk_f32 v13, v103, 0x3e0293ee, v5
	v_fmamk_f32 v14, v104, 0x3e0293ee, v5
	v_fmamk_f32 v15, v105, 0x3e0293ee, v5
	v_fmamk_f32 v96, v106, 0x3e0293ee, v5
	v_fmamk_f32 v97, v107, 0x3e0293ee, v5
	v_fmamk_f32 v98, v108, 0x3e0293ee, v5
	v_fmamk_f32 v99, v109, 0x3e0293ee, v5
	v_fmamk_f32 v100, v110, 0x3e0293ee, v5
	v_fmamk_f32 v101, v111, 0x3e0293ee, v5
	v_fmamk_f32 v112, v80, 0x3e0293ee, v5
	v_fmamk_f32 v113, v81, 0x3e0293ee, v5
	v_fmamk_f32 v114, v82, 0x3e0293ee, v5
	v_fmamk_f32 v115, v83, 0x3e0293ee, v5
	v_fmamk_f32 v116, v84, 0x3e0293ee, v5
	v_fmamk_f32 v117, v85, 0x3e0293ee, v5
	v_fmamk_f32 v118, v86, 0x3e0293ee, v5
	v_fmamk_f32 v119, v87, 0x3e0293ee, v5
	v_fmamk_f32 v120, v88, 0x3e0293ee, v5
	v_fmamk_f32 v121, v89, 0x3e0293ee, v5
	v_fmamk_f32 v122, v90, 0x3e0293ee, v5
	v_fmamk_f32 v123, v91, 0x3e0293ee, v5
	v_fmamk_f32 v124, v92, 0x3e0293ee, v5
	v_fmamk_f32 v125, v93, 0x3e0293ee, v5
	v_fmamk_f32 v126, v94, 0x3e0293ee, v5
	v_fmac_f32_e32 v5, 0x3e0293ee, v95
	v_exp_f32_e32 v127, v6
	v_exp_f32_e32 v131, v7
	v_exp_f32_e32 v132, v8
	v_exp_f32_e32 v133, v9
	v_exp_f32_e32 v10, v10
	v_exp_f32_e32 v11, v11
	v_exp_f32_e32 v12, v12
	v_exp_f32_e32 v13, v13
	v_exp_f32_e32 v14, v14
	v_exp_f32_e32 v15, v15
	v_exp_f32_e32 v134, v96
	v_exp_f32_e32 v135, v97
	v_exp_f32_e32 v136, v98
	v_exp_f32_e32 v137, v99
	v_exp_f32_e32 v138, v100
	v_exp_f32_e32 v139, v101
	s_ashr_i32 s8, s68, 8
	v_lshl_add_u32 v6, s8, 2, v128
	ds_read_b128 v[96:99], v6
	ds_read_b128 v[100:103], v6 offset:32
	ds_read_b128 v[80:83], v6 offset:128
	ds_read_b128 v[84:87], v6 offset:160
	ds_read_b128 v[104:107], v6 offset:64
	ds_read_b128 v[108:111], v6 offset:96
	ds_read_b128 v[88:91], v6 offset:192
	ds_read_b128 v[92:95], v6 offset:224
	s_add_i32 s8, s68, 0
	v_add3_u32 v140, s8, v197, v196
	v_add3_u32 v141, s8, v198, v196
	v_add3_u32 v142, s8, v199, v196
	v_add3_u32 v143, s8, v200, v196
	s_setprio 1
	ds_read_b128 v[6:9], v140 offset:49152
	ds_read_b128 v[220:223], v140 offset:57344
	ds_read_b128 v[224:227], v141 offset:49152
	ds_read_b128 v[228:231], v141 offset:57344
	ds_read_b128 v[232:235], v142 offset:49152
	s_waitcnt lgkmcnt(4)
	v_mfma_f32_32x32x16_bf16 v[96:111], v[6:9], v[172:175], v[96:111]
	ds_read_b128 v[6:9], v142 offset:57344
	s_waitcnt lgkmcnt(4)
	v_mfma_f32_32x32x16_bf16 v[80:95], v[220:223], v[172:175], v[80:95]
	ds_read_b128 v[220:223], v143 offset:49152
	s_add_i32 s8, s61, s90
	s_mov_b32 s9, m0
	s_mov_b32 m0, s8
	s_nop 0
	global_load_lds_dwordx4 v183, s[62:63]
	s_mov_b32 m0, s9
	s_waitcnt lgkmcnt(4)
	v_mfma_f32_32x32x16_bf16 v[96:111], v[224:227], v[168:171], v[96:111]
	ds_read_b128 v[224:227], v143 offset:57344
	s_waitcnt lgkmcnt(4)
	v_mfma_f32_32x32x16_bf16 v[80:95], v[228:231], v[168:171], v[80:95]
	ds_read_b128 v[228:231], v140 offset:49280
	s_waitcnt lgkmcnt(4)
	v_mfma_f32_32x32x16_bf16 v[96:111], v[232:235], v[164:167], v[96:111]
	ds_read_b128 v[232:235], v140 offset:57472
	s_addk_i32 s8, 0x400
	s_mov_b32 s9, m0
	s_mov_b32 m0, s8
	s_nop 0
	global_load_lds_dwordx4 v184, s[62:63]
	s_mov_b32 m0, s9
	s_waitcnt lgkmcnt(4)
	v_mfma_f32_32x32x16_bf16 v[80:95], v[6:9], v[164:167], v[80:95]
	ds_read_b128 v[6:9], v141 offset:49280
	s_waitcnt lgkmcnt(4)
	v_mfma_f32_32x32x16_bf16 v[96:111], v[220:223], v[160:163], v[96:111]
	ds_read_b128 v[220:223], v141 offset:57472
	s_waitcnt lgkmcnt(4)
	v_mfma_f32_32x32x16_bf16 v[80:95], v[224:227], v[160:163], v[80:95]
	ds_read_b128 v[224:227], v142 offset:49280
	s_ashr_i32 s8, s61, 6
	s_cmp_lg_u32 0, -1
	s_cselect_b32 s9, 0, 0
	s_add_i32 s8, s9, s8
	s_add_i32 s8, s8, 0x18800
	s_mov_b32 s9, m0
	s_mov_b32 m0, s8
	s_nop 0
	global_load_lds_dword v185, s[0:1]
	s_mov_b32 m0, s9
	s_waitcnt lgkmcnt(4)
	v_mfma_f32_32x32x16_bf16 v[96:111], v[228:231], v[156:159], v[96:111]
	ds_read_b128 v[228:231], v142 offset:57472
	s_waitcnt lgkmcnt(4)
	v_mfma_f32_32x32x16_bf16 v[80:95], v[232:235], v[156:159], v[80:95]
	ds_read_b128 v[232:235], v143 offset:49280
	s_waitcnt lgkmcnt(4)
	v_mfma_f32_32x32x16_bf16 v[96:111], v[6:9], v[152:155], v[96:111]
	ds_read_b128 v[6:9], v143 offset:57472
	s_add_u32 s8, s56, s66
	s_addc_u32 s9, s57, s67
	s_add_i32 s65, s53, s83
	s_mov_b32 s66, m0
	s_mov_b32 m0, s65
	s_nop 0
	global_load_lds_dwordx4 v187, s[8:9]
	s_mov_b32 m0, s66
	s_waitcnt lgkmcnt(4)
	v_mfma_f32_32x32x16_bf16 v[80:95], v[220:223], v[152:155], v[80:95]
	s_waitcnt lgkmcnt(3)
	v_mfma_f32_32x32x16_bf16 v[96:111], v[224:227], v[148:151], v[96:111]
	s_waitcnt lgkmcnt(2)
	v_mfma_f32_32x32x16_bf16 v[80:95], v[228:231], v[148:151], v[80:95]
	s_addk_i32 s65, 0x400
	s_mov_b32 s66, m0
	s_mov_b32 m0, s65
	s_nop 0
	global_load_lds_dwordx4 v186, s[8:9]
	s_mov_b32 m0, s66
	s_waitcnt lgkmcnt(1)
	v_mfma_f32_32x32x16_bf16 v[96:111], v[232:235], v[144:147], v[96:111]
	s_waitcnt lgkmcnt(0)
	v_mfma_f32_32x32x16_bf16 v[80:95], v[6:9], v[144:147], v[80:95]
	s_setprio 0
	v_exp_f32_e32 v7, v112
	v_exp_f32_e32 v112, v113
	v_exp_f32_e32 v113, v114
	v_exp_f32_e32 v114, v115
	v_exp_f32_e32 v115, v116
	v_exp_f32_e32 v116, v117
	v_exp_f32_e32 v117, v118
	v_exp_f32_e32 v118, v119
	v_exp_f32_e32 v119, v120
	v_exp_f32_e32 v120, v121
	v_exp_f32_e32 v121, v122
	v_exp_f32_e32 v122, v123
	v_exp_f32_e32 v123, v124
	v_exp_f32_e32 v124, v125
	v_exp_f32_e32 v125, v126
	v_exp_f32_e32 v126, v5
	v_add_f32_e32 v5, 0, v127
	v_add_f32_e32 v5, v131, v5
	v_add_f32_e32 v5, v132, v5
	v_add_f32_e32 v5, v133, v5
	v_add_f32_e32 v5, v10, v5
	v_add_f32_e32 v5, v11, v5
	v_add_f32_e32 v5, v12, v5
	v_add_f32_e32 v5, v13, v5
	v_add_f32_e32 v5, v14, v5
	v_add_f32_e32 v5, v15, v5
	v_add_f32_e32 v5, v134, v5
	v_add_f32_e32 v5, v135, v5
	v_add_f32_e32 v5, v136, v5
	v_add_f32_e32 v5, v137, v5
	v_add_f32_e32 v5, v138, v5
	v_add_f32_e32 v5, v139, v5
	v_add_f32_e32 v5, v7, v5
	v_add_f32_e32 v5, v112, v5
	v_add_f32_e32 v5, v113, v5
	v_add_f32_e32 v5, v114, v5
	v_add_f32_e32 v5, v115, v5
	v_add_f32_e32 v5, v116, v5
	v_add_f32_e32 v5, v117, v5
	v_add_f32_e32 v5, v118, v5
	v_add_f32_e32 v5, v119, v5
	v_add_f32_e32 v5, v120, v5
	v_add_f32_e32 v5, v121, v5
	v_add_f32_e32 v5, v122, v5
	v_add_f32_e32 v5, v123, v5
	v_add_f32_e32 v5, v124, v5
	v_add_f32_e32 v5, v125, v5
	v_add_f32_e32 v5, v126, v5
	v_mov_b32_e32 v6, v5
	s_nop 1
	v_permlane32_swap_b32_e32 v5, v6
	v_cvt_pk_bf16_f32 v8, v127, v131
	v_cvt_pk_bf16_f32 v9, v132, v133
	v_cvt_pk_bf16_f32 v10, v10, v11
	v_cvt_pk_bf16_f32 v11, v12, v13
	v_cvt_pk_bf16_f32 v12, v14, v15
	v_cvt_pk_bf16_f32 v13, v134, v135
	v_cvt_pk_bf16_f32 v14, v136, v137
	v_cvt_pk_bf16_f32 v15, v138, v139
	v_cvt_pk_bf16_f32 v112, v7, v112
	v_cvt_pk_bf16_f32 v113, v113, v114
	v_cvt_pk_bf16_f32 v114, v115, v116
	v_cvt_pk_bf16_f32 v115, v117, v118
	v_cvt_pk_bf16_f32 v116, v119, v120
	v_cvt_pk_bf16_f32 v117, v121, v122
	v_cvt_pk_bf16_f32 v118, v123, v124
	v_cvt_pk_bf16_f32 v119, v125, v126
	s_nop 0
	v_add_u32_e32 v7, s61, v193
	ds_read_b64_tr_b16 v[120:121], v7 offset:0
	ds_read_b64_tr_b16 v[122:123], v7 offset:0x800
	ds_read_b64_tr_b16 v[124:125], v7 offset:0x1000
	ds_read_b64_tr_b16 v[126:127], v7 offset:0x1800
	ds_read_b64_tr_b16 v[132:133], v7 offset:0x2000
	ds_read_b64_tr_b16 v[134:135], v7 offset:0x2800
	ds_read_b64_tr_b16 v[136:137], v7 offset:0x3000
	ds_read_b64_tr_b16 v[138:139], v7 offset:0x3800
	s_waitcnt lgkmcnt(6)
	s_nop 0
	v_mfma_f32_32x32x16_bf16 v[16:31], v[8:11], v[120:123], v[16:31]
	ds_read_b64_tr_b16 v[120:121], v7 offset:0x200
	ds_read_b64_tr_b16 v[122:123], v7 offset:0xa00
	s_waitcnt lgkmcnt(6)
	v_mfma_f32_32x32x16_bf16 v[16:31], v[12:15], v[124:127], v[16:31]
	ds_read_b64_tr_b16 v[124:125], v7 offset:0x1200
	ds_read_b64_tr_b16 v[126:127], v7 offset:0x1a00
	s_waitcnt lgkmcnt(6)
	v_mfma_f32_32x32x16_bf16 v[16:31], v[112:115], v[132:135], v[16:31]
	ds_read_b64_tr_b16 v[132:133], v7 offset:0x2200
	ds_read_b64_tr_b16 v[134:135], v7 offset:0x2a00
	s_waitcnt lgkmcnt(6)
	v_mfma_f32_32x32x16_bf16 v[16:31], v[116:119], v[136:139], v[16:31]
	ds_read_b64_tr_b16 v[136:137], v7 offset:0x3200
	ds_read_b64_tr_b16 v[138:139], v7 offset:0x3a00
	s_waitcnt lgkmcnt(6)
	v_mfma_f32_32x32x16_bf16 v[48:63], v[8:11], v[120:123], v[48:63]
	ds_read_b64_tr_b16 v[120:121], v7 offset:0x400
	ds_read_b64_tr_b16 v[122:123], v7 offset:0xc00
	s_waitcnt lgkmcnt(6)
	v_mfma_f32_32x32x16_bf16 v[48:63], v[12:15], v[124:127], v[48:63]
	ds_read_b64_tr_b16 v[124:125], v7 offset:0x1400
	ds_read_b64_tr_b16 v[126:127], v7 offset:0x1c00
	s_waitcnt lgkmcnt(6)
	v_mfma_f32_32x32x16_bf16 v[48:63], v[112:115], v[132:135], v[48:63]
	ds_read_b64_tr_b16 v[132:133], v7 offset:0x2400
	ds_read_b64_tr_b16 v[134:135], v7 offset:0x2c00
	s_waitcnt lgkmcnt(6)
	v_mfma_f32_32x32x16_bf16 v[48:63], v[116:119], v[136:139], v[48:63]
	ds_read_b64_tr_b16 v[136:137], v7 offset:0x3400
	ds_read_b64_tr_b16 v[138:139], v7 offset:0x3c00
	s_waitcnt lgkmcnt(6)
	v_mfma_f32_32x32x16_bf16 v[64:79], v[8:11], v[120:123], v[64:79]
	ds_read_b64_tr_b16 v[120:121], v7 offset:0x600
	ds_read_b64_tr_b16 v[122:123], v7 offset:0xe00
	s_waitcnt lgkmcnt(6)
	v_mfma_f32_32x32x16_bf16 v[64:79], v[12:15], v[124:127], v[64:79]
	ds_read_b64_tr_b16 v[124:125], v7 offset:0x1600
	ds_read_b64_tr_b16 v[126:127], v7 offset:0x1e00
	s_waitcnt lgkmcnt(6)
	v_mfma_f32_32x32x16_bf16 v[64:79], v[112:115], v[132:135], v[64:79]
	ds_read_b64_tr_b16 v[132:133], v7 offset:0x2600
	ds_read_b64_tr_b16 v[134:135], v7 offset:0x2e00
	s_waitcnt lgkmcnt(6)
	v_mfma_f32_32x32x16_bf16 v[64:79], v[116:119], v[136:139], v[64:79]
	ds_read_b64_tr_b16 v[136:137], v7 offset:0x3600
	ds_read_b64_tr_b16 v[138:139], v7 offset:0x3e00
	s_waitcnt lgkmcnt(6)
	v_mfma_f32_32x32x16_bf16 v[32:47], v[8:11], v[120:123], v[32:47]
	s_cmp_le_i32 s91, s69
	s_waitcnt lgkmcnt(4)
	v_mfma_f32_32x32x16_bf16 v[32:47], v[12:15], v[124:127], v[32:47]
	s_waitcnt lgkmcnt(2)
	v_mfma_f32_32x32x16_bf16 v[32:47], v[112:115], v[132:135], v[32:47]
	s_waitcnt lgkmcnt(0)
	v_mfma_f32_32x32x16_bf16 v[32:47], v[116:119], v[136:139], v[32:47]
	s_cbranch_scc1 .LBB0_1177
	v_add_u32_e32 v7, 0x4000007b, v130
	v_cmp_gt_u32_e32 vcc, 2.0, v7
	v_add_u32_e32 v7, 0x5b, v130
	s_nop 0
	v_cndmask_b32_e32 v96, v179, v96, vcc
	v_cmp_lt_u32_e32 vcc, s96, v7
	v_add_u32_e32 v7, 0x7a, v130
	s_nop 0
	v_cndmask_b32_e32 v80, v179, v80, vcc
	v_cmp_lt_u32_e32 vcc, s96, v7
	v_add_u32_e32 v7, 0x5a, v130
	s_nop 0
	v_cndmask_b32_e32 v97, v179, v97, vcc
	v_cmp_lt_u32_e32 vcc, s96, v7
	v_add_u32_e32 v7, 0x79, v130
	s_nop 0
	v_cndmask_b32_e32 v81, v179, v81, vcc
	v_cmp_lt_u32_e32 vcc, s96, v7
	v_add_u32_e32 v7, 0x59, v130
	s_nop 0
	v_cndmask_b32_e32 v98, v179, v98, vcc
	v_cmp_lt_u32_e32 vcc, s96, v7
	v_add_u32_e32 v7, 0x78, v130
	s_nop 0
	v_cndmask_b32_e32 v82, v179, v82, vcc
	v_cmp_lt_u32_e32 vcc, s96, v7
	v_add_u32_e32 v7, 0x58, v130
	s_nop 0
	v_cndmask_b32_e32 v99, v179, v99, vcc
	v_cmp_lt_u32_e32 vcc, s96, v7
	v_add_u32_e32 v7, 0x73, v130
	s_nop 0
	v_cndmask_b32_e32 v83, v179, v83, vcc
	v_cmp_lt_u32_e32 vcc, s96, v7
	v_add_u32_e32 v7, 0x53, v130
	s_nop 0
	v_cndmask_b32_e32 v100, v179, v100, vcc
	v_cmp_lt_u32_e32 vcc, s96, v7
	v_add_u32_e32 v7, 0x72, v130
	s_nop 0
	v_cndmask_b32_e32 v84, v179, v84, vcc
	v_cmp_lt_u32_e32 vcc, s96, v7
	v_add_u32_e32 v7, 0x52, v130
	s_nop 0
	v_cndmask_b32_e32 v101, v179, v101, vcc
	v_cmp_lt_u32_e32 vcc, s96, v7
	v_add_u32_e32 v7, 0x71, v130
	s_nop 0
	v_cndmask_b32_e32 v85, v179, v85, vcc
	v_cmp_lt_u32_e32 vcc, s96, v7
	v_add_u32_e32 v7, 0x51, v130
	s_nop 0
	v_cndmask_b32_e32 v102, v179, v102, vcc
	v_cmp_lt_u32_e32 vcc, s96, v7
	v_add_u32_e32 v7, 0x70, v130
	s_nop 0
	v_cndmask_b32_e32 v86, v179, v86, vcc
	v_cmp_lt_u32_e32 vcc, s96, v7
	v_add_u32_e32 v7, 0x50, v130
	s_nop 0
	v_cndmask_b32_e32 v103, v179, v103, vcc
	v_cmp_lt_u32_e32 vcc, s96, v7
	v_add_u32_e32 v7, 0x6b, v130
	s_nop 0
	v_cndmask_b32_e32 v87, v179, v87, vcc
	v_cmp_lt_u32_e32 vcc, s96, v7
	v_add_u32_e32 v7, 0x4b, v130
	s_nop 0
	v_cndmask_b32_e32 v104, v179, v104, vcc
	v_cmp_lt_u32_e32 vcc, s96, v7
	v_add_u32_e32 v7, 0x6a, v130
	s_nop 0
	v_cndmask_b32_e32 v88, v179, v88, vcc
	v_cmp_lt_u32_e32 vcc, s96, v7
	v_add_u32_e32 v7, 0x4a, v130
	s_nop 0
	v_cndmask_b32_e32 v105, v179, v105, vcc
	v_cmp_lt_u32_e32 vcc, s96, v7
	v_add_u32_e32 v7, 0x69, v130
	s_nop 0
	v_cndmask_b32_e32 v89, v179, v89, vcc
	v_cmp_lt_u32_e32 vcc, s96, v7
	v_add_u32_e32 v7, 0x49, v130
	s_nop 0
	v_cndmask_b32_e32 v106, v179, v106, vcc
	v_cmp_lt_u32_e32 vcc, s96, v7
	v_add_u32_e32 v7, 0x68, v130
	s_nop 0
	v_cndmask_b32_e32 v90, v179, v90, vcc
	v_cmp_lt_u32_e32 vcc, s96, v7
	v_add_u32_e32 v7, 0x48, v130
	s_nop 0
	v_cndmask_b32_e32 v107, v179, v107, vcc
	v_cmp_lt_u32_e32 vcc, s96, v7
	v_add_u32_e32 v7, 0x63, v130
	s_nop 0
	v_cndmask_b32_e32 v91, v179, v91, vcc
	v_cmp_lt_u32_e32 vcc, s96, v7
	v_add_u32_e32 v7, 0x43, v130
	s_nop 0
	v_cndmask_b32_e32 v108, v179, v108, vcc
	v_cmp_lt_u32_e32 vcc, s96, v7
	v_add_u32_e32 v7, 0x62, v130
	s_nop 0
	v_cndmask_b32_e32 v92, v179, v92, vcc
	v_cmp_lt_u32_e32 vcc, s96, v7
	v_add_u32_e32 v7, 0x42, v130
	s_nop 0
	v_cndmask_b32_e32 v109, v179, v109, vcc
	v_cmp_lt_u32_e32 vcc, s96, v7
	v_add_u32_e32 v7, 0x61, v130
	s_nop 0
	v_cndmask_b32_e32 v93, v179, v93, vcc
	v_cmp_lt_u32_e32 vcc, s96, v7
	v_add_u32_e32 v7, 0x41, v130
	s_nop 0
	v_cndmask_b32_e32 v110, v179, v110, vcc
	v_cmp_lt_u32_e32 vcc, s96, v7
	v_add_u32_e32 v7, 0x60, v130
	s_nop 0
	v_cndmask_b32_e32 v94, v179, v94, vcc
	v_cmp_lt_u32_e32 vcc, s96, v7
	v_add_u32_e32 v7, 64, v130
	s_nop 0
	v_cndmask_b32_e32 v111, v179, v111, vcc
	v_cmp_lt_u32_e32 vcc, s96, v7
	s_nop 1
	v_cndmask_b32_e32 v95, v179, v95, vcc
